# stack: DPP row-pass reductions + group-norm weight loads hoisted in the scan tail + QK fragment reads 12 deep in prompt attention
# baseline (speedup 1.0000x reference)
.LBB0_2056:
	v_mov_b32_e32 v96, v101
	s_load_dwordx2 s[0:1], s[40:41], 0x80
	s_add_i32 s39, s45, s38
	s_waitcnt lgkmcnt(0)
	ds_read_b128 v[204:207], v135
	ds_read_b128 v[208:211], v135 offset:32
	ds_read_b128 v[212:215], v135 offset:64
	ds_read_b128 v[216:219], v135 offset:96
	ds_read_b128 v[220:223], v135 offset:4608
	ds_read_b128 v[224:227], v135 offset:4640
	ds_read_b128 v[228:231], v135 offset:4672
	ds_read_b128 v[232:235], v135 offset:4704
	ds_read_b128 v[236:239], v135 offset:9216
	ds_read_b128 v[240:243], v135 offset:9248
	ds_read_b128 v[244:247], v135 offset:9280
	ds_read_b128 v[248:251], v135 offset:9312
	s_add_u32 s0, s0, s36
	s_addc_u32 s1, s1, s37
	s_add_i32 s38, s38, 1
	s_waitcnt lgkmcnt(11)
	v_mfma_f32_32x32x16_bf16 v[64:79], v[204:207], v[80:83], 0
	ds_read_b128 v[204:207], v135 offset:13824
	s_waitcnt lgkmcnt(11)
	v_mfma_f32_32x32x16_bf16 v[64:79], v[208:211], v[84:87], v[64:79]
	ds_read_b128 v[208:211], v135 offset:13856
	s_waitcnt lgkmcnt(11)
	v_mfma_f32_32x32x16_bf16 v[64:79], v[212:215], v[88:91], v[64:79]
	ds_read_b128 v[212:215], v135 offset:13888
	s_waitcnt lgkmcnt(11)
	v_mfma_f32_32x32x16_bf16 v[64:79], v[216:219], v[92:95], v[64:79]
	ds_read_b128 v[216:219], v135 offset:13920
	s_waitcnt lgkmcnt(11)
	v_mfma_f32_32x32x16_bf16 v[48:63], v[220:223], v[80:83], 0
	ds_read_b128 v[220:223], v135 offset:18432
	s_waitcnt lgkmcnt(11)
	v_mfma_f32_32x32x16_bf16 v[48:63], v[224:227], v[84:87], v[48:63]
	ds_read_b128 v[224:227], v135 offset:18464
	s_waitcnt lgkmcnt(11)
	v_mfma_f32_32x32x16_bf16 v[48:63], v[228:231], v[88:91], v[48:63]
	ds_read_b128 v[228:231], v135 offset:18496
	s_waitcnt lgkmcnt(11)
	v_mfma_f32_32x32x16_bf16 v[48:63], v[232:235], v[92:95], v[48:63]
	ds_read_b128 v[232:235], v135 offset:18528
	s_waitcnt lgkmcnt(11)
	v_mfma_f32_32x32x16_bf16 v[32:47], v[236:239], v[80:83], 0
	s_waitcnt lgkmcnt(10)
	v_mfma_f32_32x32x16_bf16 v[32:47], v[240:243], v[84:87], v[32:47]
	s_waitcnt lgkmcnt(9)
	v_mfma_f32_32x32x16_bf16 v[32:47], v[244:247], v[88:91], v[32:47]
	s_waitcnt lgkmcnt(8)
	v_mfma_f32_32x32x16_bf16 v[32:47], v[248:251], v[92:95], v[32:47]
	s_waitcnt lgkmcnt(7)
	v_mfma_f32_32x32x16_bf16 v[16:31], v[204:207], v[80:83], 0
	s_waitcnt lgkmcnt(6)
	v_mfma_f32_32x32x16_bf16 v[16:31], v[208:211], v[84:87], v[16:31]
	s_waitcnt lgkmcnt(5)
	v_mfma_f32_32x32x16_bf16 v[16:31], v[212:215], v[88:91], v[16:31]
	s_waitcnt lgkmcnt(4)
	v_mfma_f32_32x32x16_bf16 v[16:31], v[216:219], v[92:95], v[16:31]
	s_waitcnt lgkmcnt(3)
	v_mfma_f32_32x32x16_bf16 v[0:15], v[220:223], v[80:83], 0
	s_waitcnt lgkmcnt(2)
	v_mfma_f32_32x32x16_bf16 v[0:15], v[224:227], v[84:87], v[0:15]
	s_waitcnt lgkmcnt(1)
	v_mfma_f32_32x32x16_bf16 v[0:15], v[228:231], v[88:91], v[0:15]
	s_waitcnt lgkmcnt(0)
	v_mfma_f32_32x32x16_bf16 v[0:15], v[232:235], v[92:95], v[0:15]
	global_load_dword v80, v97, s[0:1]
	v_add_u32_e32 v94, 0x80, v96
	v_cmp_le_i32_e64 s[0:1], v100, v96
	v_cmp_gt_i32_e32 vcc, v100, v94
	s_or_b64 s[0:1], s[0:1], vcc
	v_readlane_b32 vcc_lo, v254, 37
	v_readlane_b32 vcc_hi, v254, 38
	s_or_b64 vcc, s[0:1], vcc
	v_cmp_ge_i32_e64 s[0:1], v100, v94
	v_cndmask_b32_e32 v64, v64, v200, vcc
	v_cmp_lt_i32_e32 vcc, v100, v96
	s_or_b64 s[0:1], vcc, s[0:1]
	v_readlane_b32 vcc_lo, v254, 39
	v_readlane_b32 vcc_hi, v254, 40
	s_or_b64 vcc, s[0:1], vcc
	v_cmp_gt_i32_e64 s[0:1], v104, v94
	v_cndmask_b32_e32 v65, v65, v200, vcc
	v_cmp_le_i32_e32 vcc, v104, v96
	s_or_b64 s[0:1], vcc, s[0:1]
	v_readlane_b32 vcc_lo, v254, 20
	v_readlane_b32 vcc_hi, v254, 21
	s_or_b64 vcc, s[0:1], vcc
	v_cmp_gt_i32_e64 s[0:1], v105, v94
	v_cndmask_b32_e32 v66, v66, v200, vcc
	v_cmp_le_i32_e32 vcc, v105, v96
	s_or_b64 s[0:1], vcc, s[0:1]
	v_readlane_b32 vcc_lo, v254, 18
	v_readlane_b32 vcc_hi, v254, 19
	s_or_b64 vcc, s[0:1], vcc
	v_cmp_gt_i32_e64 s[0:1], v106, v94
	v_cndmask_b32_e32 v67, v67, v200, vcc
	v_cmp_le_i32_e32 vcc, v106, v96
	s_or_b64 s[0:1], vcc, s[0:1]
	v_readlane_b32 vcc_lo, v254, 41
	v_readlane_b32 vcc_hi, v254, 42
	s_or_b64 vcc, s[0:1], vcc
	v_cmp_gt_i32_e64 s[0:1], v107, v94
	v_cndmask_b32_e32 v68, v68, v200, vcc
	v_cmp_le_i32_e32 vcc, v107, v96
	s_or_b64 s[0:1], vcc, s[0:1]
	v_readlane_b32 vcc_lo, v254, 22
	v_readlane_b32 vcc_hi, v254, 23
	s_or_b64 vcc, s[0:1], vcc
	v_cmp_gt_i32_e64 s[0:1], v108, v94
	v_cndmask_b32_e32 v69, v69, v200, vcc
	v_cmp_le_i32_e32 vcc, v108, v96
	s_or_b64 s[0:1], vcc, s[0:1]
	v_readlane_b32 vcc_lo, v254, 24
	v_readlane_b32 vcc_hi, v254, 25
	s_or_b64 vcc, s[0:1], vcc
	v_cmp_gt_i32_e64 s[0:1], v109, v94
	v_cndmask_b32_e32 v70, v70, v200, vcc
	v_cmp_le_i32_e32 vcc, v109, v96
	s_or_b64 s[0:1], vcc, s[0:1]
	v_readlane_b32 vcc_lo, v254, 26
	v_readlane_b32 vcc_hi, v254, 27
	s_or_b64 vcc, s[0:1], vcc
	v_cmp_gt_i32_e64 s[0:1], v110, v94
	v_cndmask_b32_e32 v71, v71, v200, vcc
	v_cmp_le_i32_e32 vcc, v110, v96
	s_or_b64 s[0:1], vcc, s[0:1]
	v_readlane_b32 vcc_lo, v254, 28
	v_readlane_b32 vcc_hi, v254, 29
	s_or_b64 vcc, s[0:1], vcc
	v_cmp_gt_i32_e64 s[0:1], v111, v94
	v_cndmask_b32_e32 v72, v72, v200, vcc
	v_cmp_le_i32_e32 vcc, v111, v96
	s_or_b64 s[0:1], vcc, s[0:1]
	v_readlane_b32 vcc_lo, v254, 32
	v_readlane_b32 vcc_hi, v254, 33
	s_or_b64 vcc, s[0:1], vcc
	v_cmp_gt_i32_e64 s[0:1], v112, v94
	v_cndmask_b32_e32 v73, v73, v200, vcc
	v_cmp_le_i32_e32 vcc, v112, v96
	s_or_b64 s[0:1], vcc, s[0:1]
	v_readlane_b32 vcc_lo, v254, 34
	v_readlane_b32 vcc_hi, v254, 35
	s_or_b64 vcc, s[0:1], vcc
	v_cmp_gt_i32_e64 s[0:1], v113, v94
	v_cndmask_b32_e32 v74, v74, v200, vcc
	v_cmp_le_i32_e32 vcc, v113, v96
	s_or_b64 s[0:1], vcc, s[0:1]
	v_readlane_b32 vcc_lo, v254, 5
	v_readlane_b32 vcc_hi, v254, 6
	s_or_b64 vcc, s[0:1], vcc
	v_cmp_gt_i32_e64 s[0:1], v114, v94
	v_cndmask_b32_e32 v75, v75, v200, vcc
	v_cmp_le_i32_e32 vcc, v114, v96
	s_or_b64 s[0:1], vcc, s[0:1]
	v_readlane_b32 vcc_lo, v254, 8
	v_readlane_b32 vcc_hi, v254, 9
	s_or_b64 vcc, s[0:1], vcc
	v_cmp_gt_i32_e64 s[0:1], v115, v94
	v_cndmask_b32_e32 v76, v76, v200, vcc
	v_cmp_le_i32_e32 vcc, v115, v96
	s_or_b64 s[0:1], vcc, s[0:1]
	v_readlane_b32 vcc_lo, v254, 30
	v_readlane_b32 vcc_hi, v254, 31
	s_or_b64 vcc, s[0:1], vcc
	v_cmp_gt_i32_e64 s[0:1], v116, v94
	v_cndmask_b32_e32 v77, v77, v200, vcc
	v_cmp_le_i32_e32 vcc, v116, v96
	s_or_b64 s[0:1], vcc, s[0:1]
	v_readlane_b32 vcc_lo, v254, 58
	v_readlane_b32 vcc_hi, v254, 59
	s_or_b64 vcc, s[0:1], vcc
	v_cmp_gt_i32_e64 s[0:1], v117, v94
	v_cndmask_b32_e32 v85, v78, v200, vcc
	v_cmp_le_i32_e32 vcc, v117, v96
	s_or_b64 s[0:1], vcc, s[0:1]
	v_readlane_b32 vcc_lo, v254, 60
	v_readlane_b32 vcc_hi, v254, 61
	s_or_b64 vcc, s[0:1], vcc
	v_readlane_b32 s0, v254, 62
	v_readlane_b32 s1, v254, 63
	s_waitcnt vmcnt(0)
	v_max3_f32 v81, v80, v64, v65
	v_max3_f32 v81, v81, v66, v67
	v_cndmask_b32_e64 v93, v48, v200, s[0:1]
	v_readlane_b32 s0, v255, 0
	v_readlane_b32 s1, v255, 1
	v_max3_f32 v81, v81, v68, v69
	v_max3_f32 v81, v81, v70, v71
	v_cndmask_b32_e64 v90, v49, v200, s[0:1]
	v_readlane_b32 s0, v255, 2
	v_readlane_b32 s1, v255, 3
	v_max3_f32 v81, v81, v72, v73
	v_max3_f32 v81, v81, v74, v75
	v_cndmask_b32_e64 v91, v50, v200, s[0:1]
	v_readlane_b32 s0, v255, 4
	v_readlane_b32 s1, v255, 5
	v_max3_f32 v81, v81, v76, v77
	v_cndmask_b32_e32 v92, v79, v200, vcc
	v_cndmask_b32_e64 v88, v51, v200, s[0:1]
	v_readlane_b32 s0, v255, 6
	v_readlane_b32 s1, v255, 7
	v_max3_f32 v78, v81, v85, v92
	v_max3_f32 v48, v78, v93, v90
	v_cndmask_b32_e64 v89, v52, v200, s[0:1]
	v_readlane_b32 s0, v255, 8
	v_readlane_b32 s1, v255, 9
	v_cmp_le_i32_e32 vcc, v118, v96
	v_max3_f32 v48, v48, v91, v88
	v_cndmask_b32_e64 v86, v53, v200, s[0:1]
	v_readlane_b32 s0, v255, 10
	v_readlane_b32 s1, v255, 11
	v_max3_f32 v48, v48, v89, v86
	v_cndmask_b32_e64 v52, v39, v200, s[6:7]
	v_cndmask_b32_e64 v87, v54, v200, s[0:1]
	v_readlane_b32 s0, v255, 12
	v_readlane_b32 s1, v255, 13
	v_cndmask_b32_e64 v51, v40, v200, s[50:51]
	v_cndmask_b32_e64 v50, v41, v200, s[52:53]
	v_cndmask_b32_e64 v83, v55, v200, s[0:1]
	v_readlane_b32 s0, v255, 14
	v_readlane_b32 s1, v255, 15
	v_max3_f32 v48, v48, v87, v83
	v_cndmask_b32_e64 v49, v42, v200, s[54:55]
	v_cndmask_b32_e64 v84, v56, v200, s[0:1]
	v_readlane_b32 s0, v255, 16
	v_readlane_b32 s1, v255, 17
	v_cndmask_b32_e64 v42, v45, v200, s[60:61]
	v_cndmask_b32_e64 v41, v46, v200, s[62:63]
	v_cndmask_b32_e64 v81, v57, v200, s[0:1]
	v_readlane_b32 s0, v255, 18
	v_readlane_b32 s1, v255, 19
	v_max3_f32 v48, v48, v84, v81
	v_cndmask_b32_e64 v40, v47, v200, s[64:65]
	v_cndmask_b32_e64 v82, v58, v200, s[0:1]
	v_readlane_b32 s0, v255, 20
	v_readlane_b32 s1, v255, 21
	v_cndmask_b32_e64 v39, v16, v200, s[66:67]
	s_nop 0
	v_cndmask_b32_e64 v78, v59, v200, s[0:1]
	v_readlane_b32 s0, v255, 22
	v_readlane_b32 s1, v255, 23
	v_max3_f32 v48, v48, v82, v78
	s_nop 0
	v_cndmask_b32_e64 v79, v60, v200, s[0:1]
	v_readlane_b32 s0, v255, 24
	v_readlane_b32 s1, v255, 25
	s_nop 1
	v_cndmask_b32_e64 v61, v61, v200, s[0:1]
	v_readlane_b32 s0, v255, 26
	v_readlane_b32 s1, v255, 27
	v_max3_f32 v48, v48, v79, v61
	s_nop 0
	v_cndmask_b32_e64 v62, v62, v200, s[0:1]
	v_readlane_b32 s0, v255, 28
	v_readlane_b32 s1, v255, 29
	s_nop 1
	v_cndmask_b32_e64 v59, v63, v200, s[0:1]
	v_readlane_b32 s0, v255, 30
	v_readlane_b32 s1, v255, 31
	v_max3_f32 v48, v48, v62, v59
	s_nop 0
	v_cndmask_b32_e64 v60, v32, v200, s[0:1]
	v_readlane_b32 s0, v255, 32
	v_readlane_b32 s1, v255, 33
	s_nop 1
	v_cndmask_b32_e64 v57, v33, v200, s[0:1]
	v_readlane_b32 s0, v255, 34
	v_readlane_b32 s1, v255, 35
	v_max3_f32 v32, v48, v60, v57
	v_cndmask_b32_e64 v48, v43, v200, s[56:57]
	v_cndmask_b32_e64 v58, v34, v200, s[0:1]
	v_readlane_b32 s0, v255, 36
	v_readlane_b32 s1, v255, 37
	v_cndmask_b32_e64 v43, v44, v200, s[58:59]
	v_cndmask_b32_e64 v34, v21, v200, s[76:77]
	v_cndmask_b32_e64 v55, v35, v200, s[0:1]
	v_readlane_b32 s0, v255, 38
	v_readlane_b32 s1, v255, 39
	v_max3_f32 v32, v32, v58, v55
	v_cndmask_b32_e64 v35, v20, v200, s[74:75]
	v_cndmask_b32_e64 v56, v36, v200, s[0:1]
	v_readlane_b32 s0, v255, 40
	v_readlane_b32 s1, v255, 41
	v_cndmask_b32_e64 v36, v19, v200, s[72:73]
	v_cndmask_b32_e64 v33, v22, v200, s[78:79]
	v_cndmask_b32_e64 v53, v37, v200, s[0:1]
	v_readlane_b32 s0, v255, 42
	v_readlane_b32 s1, v255, 43
	v_max3_f32 v32, v32, v56, v53
	v_cndmask_b32_e64 v37, v18, v200, s[70:71]
	v_cndmask_b32_e64 v54, v38, v200, s[0:1]
	v_cmp_gt_i32_e64 s[0:1], v100, v96
	s_or_b64 s[0:1], vcc, s[0:1]
	s_or_b64 vcc, s[0:1], s[42:43]
	v_cndmask_b32_e32 v0, v0, v200, vcc
	v_cmp_le_i32_e32 vcc, v119, v96
	v_cmp_gt_i32_e64 s[0:1], v119, v94
	s_or_b64 s[0:1], vcc, s[0:1]
	s_or_b64 vcc, s[0:1], s[4:5]
	v_cndmask_b32_e32 v1, v1, v200, vcc
	v_cmp_le_i32_e32 vcc, v120, v96
	v_cmp_gt_i32_e64 s[0:1], v120, v94
	s_or_b64 s[0:1], vcc, s[0:1]
	s_or_b64 vcc, s[0:1], s[48:49]
	v_cndmask_b32_e32 v2, v2, v200, vcc
	v_cmp_le_i32_e32 vcc, v121, v96
	v_cmp_gt_i32_e64 s[0:1], v121, v94
	s_or_b64 s[0:1], vcc, s[0:1]
	s_or_b64 vcc, s[0:1], s[8:9]
	v_cndmask_b32_e32 v3, v3, v200, vcc
	v_cmp_le_i32_e32 vcc, v122, v96
	v_cmp_gt_i32_e64 s[0:1], v122, v94
	s_or_b64 s[0:1], vcc, s[0:1]
	s_or_b64 vcc, s[0:1], s[10:11]
	v_cndmask_b32_e32 v4, v4, v200, vcc
	v_cmp_le_i32_e32 vcc, v123, v96
	v_cmp_gt_i32_e64 s[0:1], v123, v94
	s_or_b64 s[0:1], vcc, s[0:1]
	s_or_b64 vcc, s[0:1], s[12:13]
	v_cndmask_b32_e32 v5, v5, v200, vcc
	v_cmp_le_i32_e32 vcc, v124, v96
	v_cmp_gt_i32_e64 s[0:1], v124, v94
	s_or_b64 s[0:1], vcc, s[0:1]
	s_or_b64 vcc, s[0:1], s[14:15]
	v_cndmask_b32_e32 v6, v6, v200, vcc
	v_cmp_le_i32_e32 vcc, v125, v96
	v_cmp_gt_i32_e64 s[0:1], v125, v94
	s_or_b64 s[0:1], vcc, s[0:1]
	s_or_b64 vcc, s[0:1], s[16:17]
	v_cndmask_b32_e32 v7, v7, v200, vcc
	v_cmp_le_i32_e32 vcc, v126, v96
	v_cmp_gt_i32_e64 s[0:1], v126, v94
	s_or_b64 s[0:1], vcc, s[0:1]
	s_or_b64 vcc, s[0:1], s[18:19]
	v_cndmask_b32_e32 v8, v8, v200, vcc
	v_cmp_le_i32_e32 vcc, v127, v96
	v_cmp_gt_i32_e64 s[0:1], v127, v94
	s_or_b64 s[0:1], vcc, s[0:1]
	s_or_b64 vcc, s[0:1], s[20:21]
	v_max3_f32 v32, v32, v54, v52
	v_cndmask_b32_e32 v9, v9, v200, vcc
	v_cmp_le_i32_e32 vcc, v128, v96
	v_cmp_gt_i32_e64 s[0:1], v128, v94
	v_max3_f32 v32, v32, v51, v50
	s_or_b64 s[0:1], vcc, s[0:1]
	v_max3_f32 v32, v32, v49, v48
	s_or_b64 vcc, s[0:1], s[22:23]
	v_max3_f32 v32, v32, v43, v42
	v_cndmask_b32_e32 v10, v10, v200, vcc
	v_cmp_le_i32_e32 vcc, v129, v96
	v_cmp_gt_i32_e64 s[0:1], v129, v94
	v_max3_f32 v32, v32, v41, v40
	v_cndmask_b32_e64 v38, v17, v200, s[68:69]
	s_or_b64 s[0:1], vcc, s[0:1]
	v_max3_f32 v16, v32, v39, v38
	s_or_b64 vcc, s[0:1], s[24:25]
	v_max3_f32 v16, v16, v37, v36
	v_cndmask_b32_e32 v11, v11, v200, vcc
	v_cmp_le_i32_e32 vcc, v130, v96
	v_cmp_gt_i32_e64 s[0:1], v130, v94
	v_max3_f32 v16, v16, v35, v34
	v_cndmask_b32_e64 v32, v23, v200, s[80:81]
	s_or_b64 s[0:1], vcc, s[0:1]
	v_max3_f32 v16, v16, v33, v32
	v_cndmask_b32_e64 v23, v24, v200, s[82:83]
	v_cndmask_b32_e64 v22, v25, v200, s[84:85]
	s_or_b64 vcc, s[0:1], s[26:27]
	v_max3_f32 v16, v16, v23, v22
	v_cndmask_b32_e64 v21, v26, v200, s[86:87]
	v_cndmask_b32_e64 v20, v27, v200, s[88:89]
	v_cndmask_b32_e32 v12, v12, v200, vcc
	v_cmp_le_i32_e32 vcc, v131, v96
	v_cmp_gt_i32_e64 s[0:1], v131, v94
	v_max3_f32 v16, v16, v21, v20
	v_cndmask_b32_e64 v19, v28, v200, s[90:91]
	v_cndmask_b32_e64 v18, v29, v200, s[92:93]
	s_or_b64 s[0:1], vcc, s[0:1]
	v_max3_f32 v24, v16, v19, v18
	v_cndmask_b32_e64 v17, v30, v200, s[94:95]
	v_cndmask_b32_e64 v16, v31, v200, s[96:97]
	s_or_b64 vcc, s[0:1], s[28:29]
	v_max3_f32 v24, v24, v17, v16
	v_cndmask_b32_e32 v13, v13, v200, vcc
	v_cmp_le_i32_e32 vcc, v132, v96
	v_cmp_gt_i32_e64 s[0:1], v132, v94
	v_max3_f32 v24, v24, v0, v1
	s_or_b64 s[0:1], vcc, s[0:1]
	v_max3_f32 v24, v24, v2, v3
	s_or_b64 vcc, s[0:1], s[30:31]
	v_max3_f32 v24, v24, v4, v5
	v_cndmask_b32_e32 v14, v14, v200, vcc
	v_cmp_le_i32_e32 vcc, v133, v96
	v_cmp_gt_i32_e64 s[0:1], v133, v94
	v_max3_f32 v24, v24, v6, v7
	s_or_b64 s[0:1], vcc, s[0:1]
	v_and_b32_e32 v26, 64, v198
	v_max3_f32 v24, v24, v8, v9
	s_or_b64 vcc, s[0:1], s[34:35]
	v_xor_b32_e32 v25, 32, v198
	v_add_u32_e32 v26, 64, v26
	v_max3_f32 v24, v24, v10, v11
	v_cndmask_b32_e32 v15, v15, v200, vcc
	v_cmp_lt_i32_e32 vcc, v25, v26
	v_max3_f32 v24, v24, v12, v13
	v_max3_f32 v24, v24, v14, v15
	v_cndmask_b32_e32 v25, v198, v25, vcc
	v_lshlrev_b32_e32 v25, 2, v25
	ds_bpermute_b32 v26, v25, v24
	s_lshr_b32 s1, s39, 2
	s_mulk_i32 s1, 0x4080
	s_add_i32 s2, s1, 0x20400
	s_add_i32 s0, s44, s33
	s_waitcnt lgkmcnt(0)
	v_max_f32_e32 v26, v26, v26
	v_max_f32_e32 v24, v24, v26
	v_sub_f32_e32 v26, v64, v24
	v_mul_f32_e32 v26, 0x3fb8aa3b, v26
	v_sub_f32_e32 v28, v65, v24
	v_exp_f32_e32 v26, v26
	v_mul_f32_e32 v28, 0x3fb8aa3b, v28
	v_sub_f32_e32 v29, v66, v24
	v_exp_f32_e32 v28, v28
	v_mul_f32_e32 v29, 0x3fb8aa3b, v29
	v_sub_f32_e32 v30, v67, v24
	v_exp_f32_e32 v29, v29
	v_mul_f32_e32 v30, 0x3fb8aa3b, v30
	v_sub_f32_e32 v31, v68, v24
	v_exp_f32_e32 v30, v30
	v_mul_f32_e32 v31, 0x3fb8aa3b, v31
	v_sub_f32_e32 v44, v69, v24
	v_add_f32_e32 v27, 0, v26
	v_exp_f32_e32 v31, v31
	v_mul_f32_e32 v44, 0x3fb8aa3b, v44
	v_sub_f32_e32 v45, v70, v24
	v_add_f32_e32 v27, v28, v27
	v_exp_f32_e32 v44, v44
	v_mul_f32_e32 v45, 0x3fb8aa3b, v45
	v_sub_f32_e32 v46, v71, v24
	v_add_f32_e32 v27, v29, v27
	v_exp_f32_e32 v45, v45
	v_mul_f32_e32 v46, 0x3fb8aa3b, v46
	v_sub_f32_e32 v47, v72, v24
	v_add_f32_e32 v27, v30, v27
	v_exp_f32_e32 v46, v46
	v_mul_f32_e32 v47, 0x3fb8aa3b, v47
	v_sub_f32_e32 v63, v73, v24
	v_add_f32_e32 v27, v31, v27
	v_exp_f32_e32 v47, v47
	v_mul_f32_e32 v63, 0x3fb8aa3b, v63
	v_sub_f32_e32 v64, v74, v24
	v_add_f32_e32 v27, v44, v27
	v_exp_f32_e32 v63, v63
	v_mul_f32_e32 v64, 0x3fb8aa3b, v64
	v_sub_f32_e32 v65, v75, v24
	v_add_f32_e32 v27, v45, v27
	v_exp_f32_e32 v64, v64
	v_mul_f32_e32 v65, 0x3fb8aa3b, v65
	v_sub_f32_e32 v66, v76, v24
	v_add_f32_e32 v27, v46, v27
	v_exp_f32_e32 v65, v65
	v_mul_f32_e32 v66, 0x3fb8aa3b, v66
	v_sub_f32_e32 v67, v77, v24
	v_add_f32_e32 v27, v47, v27
	v_exp_f32_e32 v66, v66
	v_mul_f32_e32 v67, 0x3fb8aa3b, v67
	v_sub_f32_e32 v68, v85, v24
	v_add_f32_e32 v27, v63, v27
	v_exp_f32_e32 v67, v67
	v_mul_f32_e32 v68, 0x3fb8aa3b, v68
	v_sub_f32_e32 v69, v92, v24
	v_add_f32_e32 v27, v64, v27
	v_exp_f32_e32 v68, v68
	v_mul_f32_e32 v69, 0x3fb8aa3b, v69
	v_sub_f32_e32 v70, v93, v24
	v_add_f32_e32 v27, v65, v27
	v_exp_f32_e32 v69, v69
	v_mul_f32_e32 v70, 0x3fb8aa3b, v70
	v_sub_f32_e32 v71, v90, v24
	v_add_f32_e32 v27, v66, v27
	v_exp_f32_e32 v70, v70
	v_mul_f32_e32 v71, 0x3fb8aa3b, v71
	v_sub_f32_e32 v72, v91, v24
	v_add_f32_e32 v27, v67, v27
	v_exp_f32_e32 v71, v71
	v_mul_f32_e32 v72, 0x3fb8aa3b, v72
	v_sub_f32_e32 v73, v88, v24
	v_add_f32_e32 v27, v68, v27
	v_exp_f32_e32 v72, v72
	v_mul_f32_e32 v73, 0x3fb8aa3b, v73
	v_sub_f32_e32 v74, v89, v24
	v_add_f32_e32 v27, v69, v27
	v_exp_f32_e32 v73, v73
	v_mul_f32_e32 v74, 0x3fb8aa3b, v74
	v_sub_f32_e32 v75, v86, v24
	v_add_f32_e32 v27, v70, v27
	v_exp_f32_e32 v74, v74
	v_mul_f32_e32 v75, 0x3fb8aa3b, v75
	v_sub_f32_e32 v76, v87, v24
	v_add_f32_e32 v27, v71, v27
	v_exp_f32_e32 v75, v75
	v_mul_f32_e32 v76, 0x3fb8aa3b, v76
	v_sub_f32_e32 v77, v83, v24
	v_add_f32_e32 v27, v72, v27
	v_exp_f32_e32 v76, v76
	v_mul_f32_e32 v77, 0x3fb8aa3b, v77
	v_sub_f32_e32 v83, v84, v24
	v_add_f32_e32 v27, v73, v27
	v_exp_f32_e32 v77, v77
	v_mul_f32_e32 v83, 0x3fb8aa3b, v83
	v_sub_f32_e32 v81, v81, v24
	v_add_f32_e32 v27, v74, v27
	v_exp_f32_e32 v83, v83
	v_mul_f32_e32 v81, 0x3fb8aa3b, v81
	v_sub_f32_e32 v82, v82, v24
	v_add_f32_e32 v27, v75, v27
	v_exp_f32_e32 v81, v81
	v_mul_f32_e32 v82, 0x3fb8aa3b, v82
	v_sub_f32_e32 v78, v78, v24
	v_add_f32_e32 v27, v76, v27
	v_exp_f32_e32 v82, v82
	v_mul_f32_e32 v78, 0x3fb8aa3b, v78
	v_sub_f32_e32 v79, v79, v24
	v_add_f32_e32 v27, v77, v27
	v_exp_f32_e32 v78, v78
	v_mul_f32_e32 v79, 0x3fb8aa3b, v79
	v_sub_f32_e32 v61, v61, v24
	v_add_f32_e32 v27, v83, v27
	v_exp_f32_e32 v79, v79
	v_mul_f32_e32 v61, 0x3fb8aa3b, v61
	v_sub_f32_e32 v62, v62, v24
	v_add_f32_e32 v27, v81, v27
	v_exp_f32_e32 v61, v61
	v_mul_f32_e32 v62, 0x3fb8aa3b, v62
	v_sub_f32_e32 v59, v59, v24
	v_add_f32_e32 v27, v82, v27
	v_exp_f32_e32 v62, v62
	v_mul_f32_e32 v59, 0x3fb8aa3b, v59
	v_sub_f32_e32 v60, v60, v24
	v_add_f32_e32 v27, v78, v27
	v_exp_f32_e32 v59, v59
	v_mul_f32_e32 v60, 0x3fb8aa3b, v60
	v_sub_f32_e32 v57, v57, v24
	v_add_f32_e32 v27, v79, v27
	v_exp_f32_e32 v60, v60
	v_mul_f32_e32 v57, 0x3fb8aa3b, v57
	v_sub_f32_e32 v58, v58, v24
	v_add_f32_e32 v27, v61, v27
	v_exp_f32_e32 v57, v57
	v_mul_f32_e32 v58, 0x3fb8aa3b, v58
	v_sub_f32_e32 v55, v55, v24
	v_add_f32_e32 v27, v62, v27
	v_exp_f32_e32 v58, v58
	v_mul_f32_e32 v55, 0x3fb8aa3b, v55
	v_sub_f32_e32 v56, v56, v24
	v_add_f32_e32 v27, v59, v27
	v_exp_f32_e32 v55, v55
	v_mul_f32_e32 v56, 0x3fb8aa3b, v56
	v_sub_f32_e32 v53, v53, v24
	v_add_f32_e32 v27, v60, v27
	v_exp_f32_e32 v56, v56
	v_mul_f32_e32 v53, 0x3fb8aa3b, v53
	v_sub_f32_e32 v54, v54, v24
	v_add_f32_e32 v27, v57, v27
	v_exp_f32_e32 v53, v53
	v_mul_f32_e32 v54, 0x3fb8aa3b, v54
	v_sub_f32_e32 v52, v52, v24
	v_add_f32_e32 v27, v58, v27
	v_exp_f32_e32 v54, v54
	v_mul_f32_e32 v52, 0x3fb8aa3b, v52
	v_sub_f32_e32 v51, v51, v24
	v_add_f32_e32 v27, v55, v27
	v_exp_f32_e32 v52, v52
	v_mul_f32_e32 v51, 0x3fb8aa3b, v51
	v_sub_f32_e32 v50, v50, v24
	v_add_f32_e32 v27, v56, v27
	v_exp_f32_e32 v51, v51
	v_mul_f32_e32 v50, 0x3fb8aa3b, v50
	v_sub_f32_e32 v49, v49, v24
	v_add_f32_e32 v27, v53, v27
	v_exp_f32_e32 v50, v50
	v_mul_f32_e32 v49, 0x3fb8aa3b, v49
	v_sub_f32_e32 v48, v48, v24
	v_add_f32_e32 v27, v54, v27
	v_exp_f32_e32 v49, v49
	v_mul_f32_e32 v48, 0x3fb8aa3b, v48
	v_sub_f32_e32 v43, v43, v24
	v_add_f32_e32 v27, v52, v27
	v_exp_f32_e32 v48, v48
	v_mul_f32_e32 v43, 0x3fb8aa3b, v43
	v_sub_f32_e32 v42, v42, v24
	v_add_f32_e32 v27, v51, v27
	v_exp_f32_e32 v84, v43
	v_mul_f32_e32 v42, 0x3fb8aa3b, v42
	v_sub_f32_e32 v41, v41, v24
	v_add_f32_e32 v27, v50, v27
	v_exp_f32_e32 v85, v42
	v_mul_f32_e32 v41, 0x3fb8aa3b, v41
	v_sub_f32_e32 v40, v40, v24
	v_add_f32_e32 v27, v49, v27
	v_exp_f32_e32 v86, v41
	v_mul_f32_e32 v40, 0x3fb8aa3b, v40
	v_sub_f32_e32 v39, v39, v24
	v_add_f32_e32 v27, v48, v27
	v_exp_f32_e32 v87, v40
	v_mul_f32_e32 v39, 0x3fb8aa3b, v39
	v_sub_f32_e32 v38, v38, v24
	v_add_f32_e32 v27, v84, v27
	v_exp_f32_e32 v88, v39
	v_mul_f32_e32 v38, 0x3fb8aa3b, v38
	v_sub_f32_e32 v37, v37, v24
	v_add_f32_e32 v27, v85, v27
	v_exp_f32_e32 v89, v38
	v_mul_f32_e32 v37, 0x3fb8aa3b, v37
	v_sub_f32_e32 v36, v36, v24
	v_sub_f32_e32 v1, v1, v24
	v_add_f32_e32 v27, v86, v27
	v_exp_f32_e32 v90, v37
	v_mul_f32_e32 v36, 0x3fb8aa3b, v36
	v_sub_f32_e32 v35, v35, v24
	v_mul_f32_e32 v1, 0x3fb8aa3b, v1
	v_add_f32_e32 v27, v87, v27
	v_exp_f32_e32 v91, v36
	v_mul_f32_e32 v35, 0x3fb8aa3b, v35
	v_sub_f32_e32 v34, v34, v24
	v_exp_f32_e32 v142, v1
	v_sub_f32_e32 v1, v2, v24
	v_add_f32_e32 v27, v88, v27
	v_exp_f32_e32 v35, v35
	v_mul_f32_e32 v34, 0x3fb8aa3b, v34
	v_sub_f32_e32 v33, v33, v24
	v_mul_f32_e32 v1, 0x3fb8aa3b, v1
	v_add_f32_e32 v27, v89, v27
	v_exp_f32_e32 v92, v34
	v_mul_f32_e32 v33, 0x3fb8aa3b, v33
	v_sub_f32_e32 v32, v32, v24
	v_exp_f32_e32 v143, v1
	v_sub_f32_e32 v1, v3, v24
	v_add_f32_e32 v27, v90, v27
	v_exp_f32_e32 v33, v33
	v_mul_f32_e32 v32, 0x3fb8aa3b, v32
	v_sub_f32_e32 v23, v23, v24
	v_mul_f32_e32 v1, 0x3fb8aa3b, v1
	v_add_f32_e32 v27, v91, v27
	v_exp_f32_e32 v32, v32
	v_mul_f32_e32 v23, 0x3fb8aa3b, v23
	v_sub_f32_e32 v22, v22, v24
	v_exp_f32_e32 v144, v1
	v_sub_f32_e32 v1, v4, v24
	v_add_f32_e32 v27, v35, v27
	v_exp_f32_e32 v93, v23
	v_mul_f32_e32 v22, 0x3fb8aa3b, v22
	v_sub_f32_e32 v21, v21, v24
	v_mul_f32_e32 v1, 0x3fb8aa3b, v1
	v_add_f32_e32 v27, v92, v27
	v_exp_f32_e32 v94, v22
	v_mul_f32_e32 v21, 0x3fb8aa3b, v21
	v_sub_f32_e32 v20, v20, v24
	v_exp_f32_e32 v145, v1
	v_sub_f32_e32 v1, v5, v24
	v_add_f32_e32 v27, v33, v27
	v_exp_f32_e32 v95, v21
	v_mul_f32_e32 v20, 0x3fb8aa3b, v20
	v_sub_f32_e32 v19, v19, v24
	v_mul_f32_e32 v1, 0x3fb8aa3b, v1
	v_add_f32_e32 v27, v32, v27
	v_exp_f32_e32 v96, v20
	v_mul_f32_e32 v19, 0x3fb8aa3b, v19
	v_sub_f32_e32 v18, v18, v24
	v_exp_f32_e32 v146, v1
	v_sub_f32_e32 v1, v6, v24
	v_add_f32_e32 v23, v93, v27
	v_exp_f32_e32 v137, v19
	v_mul_f32_e32 v18, 0x3fb8aa3b, v18
	v_sub_f32_e32 v17, v17, v24
	v_mul_f32_e32 v1, 0x3fb8aa3b, v1
	v_add_f32_e32 v22, v94, v23
	v_exp_f32_e32 v138, v18
	v_mul_f32_e32 v17, 0x3fb8aa3b, v17
	v_sub_f32_e32 v16, v16, v24
	v_exp_f32_e32 v147, v1
	v_sub_f32_e32 v1, v7, v24
	v_add_f32_e32 v21, v95, v22
	v_exp_f32_e32 v139, v17
	v_mul_f32_e32 v16, 0x3fb8aa3b, v16
	v_sub_f32_e32 v0, v0, v24
	v_mul_f32_e32 v1, 0x3fb8aa3b, v1
	v_add_f32_e32 v20, v96, v21
	v_exp_f32_e32 v140, v16
	v_mul_f32_e32 v0, 0x3fb8aa3b, v0
	v_exp_f32_e32 v148, v1
	v_sub_f32_e32 v1, v8, v24
	v_add_f32_e32 v19, v137, v20
	v_exp_f32_e32 v141, v0
	v_mul_f32_e32 v1, 0x3fb8aa3b, v1
	v_add_f32_e32 v18, v138, v19
	v_exp_f32_e32 v149, v1
	v_sub_f32_e32 v1, v9, v24
	v_add_f32_e32 v17, v139, v18
	v_mul_f32_e32 v1, 0x3fb8aa3b, v1
	v_add_f32_e32 v16, v140, v17
	v_exp_f32_e32 v150, v1
	v_sub_f32_e32 v1, v10, v24
	v_add_f32_e32 v0, v141, v16
	v_mul_f32_e32 v1, 0x3fb8aa3b, v1
	v_add_f32_e32 v0, v142, v0
	v_exp_f32_e32 v151, v1
	v_sub_f32_e32 v1, v11, v24
	v_add_f32_e32 v0, v143, v0
	v_mul_f32_e32 v1, 0x3fb8aa3b, v1
	v_add_f32_e32 v0, v144, v0
	v_exp_f32_e32 v152, v1
	v_sub_f32_e32 v1, v12, v24
	v_add_f32_e32 v0, v145, v0
	v_mul_f32_e32 v1, 0x3fb8aa3b, v1
	v_add_f32_e32 v0, v146, v0
	v_exp_f32_e32 v153, v1
	v_sub_f32_e32 v1, v13, v24
	v_add_f32_e32 v0, v147, v0
	v_mul_f32_e32 v1, 0x3fb8aa3b, v1
	v_add_f32_e32 v0, v148, v0
	v_exp_f32_e32 v154, v1
	v_sub_f32_e32 v1, v14, v24
	v_add_f32_e32 v0, v149, v0
	v_mul_f32_e32 v1, 0x3fb8aa3b, v1
	v_add_f32_e32 v0, v150, v0
	v_exp_f32_e32 v155, v1
	v_sub_f32_e32 v1, v15, v24
	v_add_f32_e32 v0, v151, v0
	v_mul_f32_e32 v1, 0x3fb8aa3b, v1
	v_add_f32_e32 v0, v152, v0
	v_exp_f32_e32 v156, v1
	v_add_f32_e32 v0, v153, v0
	v_add_f32_e32 v0, v154, v0
	v_add_f32_e32 v0, v155, v0
	v_add_f32_e32 v0, v156, v0
	ds_bpermute_b32 v1, v25, v0
	v_cvt_pk_bf16_f32 v2, v31, v44
	v_add_u32_e32 v44, 0x9000, v136
	ds_read2_b64 v[4:7], v44 offset1:2
	ds_read2_b64 v[36:39], v44 offset0:4 offset1:6
	v_cvt_pk_bf16_f32 v3, v45, v46
	s_waitcnt lgkmcnt(2)
	v_add_f32_e32 v0, v0, v1
	v_sub_f32_e32 v1, v80, v24
	v_mul_f32_e32 v1, 0x3fb8aa3b, v1
	v_exp_f32_e32 v1, v1
	v_add_u32_e32 v45, 0xd000, v136
	v_cvt_pk_bf16_f32 v40, v47, v63
	v_cvt_pk_bf16_f32 v41, v64, v65
	v_add_f32_e32 v34, v1, v0
	v_cvt_pk_bf16_f32 v0, v26, v28
	v_cvt_pk_bf16_f32 v1, v29, v30
	v_cvt_pk_bf16_f32 v42, v66, v67
	v_cvt_pk_bf16_f32 v43, v68, v69
	s_waitcnt lgkmcnt(1)
	v_mfma_f32_32x32x16_bf16 v[16:31], v[4:7], v[0:3], 0
	ds_read2_b64 v[4:7], v45 offset0:96 offset1:98
	s_and_b32 s0, s0, 0xc0
	s_mov_b64 vcc, s[46:47]
	v_readlane_b32 s1, v254, 36
	s_add_i32 s33, s33, 64
	v_mov_b32_e32 v203, 0
	v_lshl_add_u64 v[192:193], s[2:3], 0, v[98:99]
	v_lshlrev_b64 v[192:193], 9, v[192:193]
	v_lshl_add_u64 v[192:193], vcc, 0, v[192:193]
	s_lshl_b32 s2, s0, 1
	v_lshl_add_u64 v[192:193], v[192:193], 0, s[2:3]
	s_and_b32 s0, s38, 4
	s_or_b32 s0, s0, s1
	s_lshr_b32 s0, s0, 2
	v_lshlrev_b32_e32 v202, 1, v100
	v_lshl_add_u64 v[192:193], v[192:193], 0, v[202:203]
	s_mul_i32 s2, s0, 0x4080
	v_lshl_add_u64 v[194:195], s[2:3], 0, v[98:99]
	s_and_b32 s0, s33, 0xc0
	v_or_b32_e32 v196, s0, v134
	v_lshlrev_b64 v[194:195], 9, v[194:195]
	v_lshl_add_u64 v[194:195], vcc, 0, v[194:195]
	v_lshlrev_b32_e32 v202, 1, v196
	v_lshl_add_u64 v[194:195], v[194:195], 0, v[202:203]
	global_load_dwordx2 v[160:161], v[192:193], off
	global_load_dwordx2 v[162:163], v[192:193], off offset:16
	global_load_dwordx2 v[164:165], v[192:193], off offset:32
	global_load_dwordx2 v[166:167], v[192:193], off offset:48
	global_load_dwordx2 v[168:169], v[192:193], off offset:64
	global_load_dwordx2 v[170:171], v[192:193], off offset:80
	global_load_dwordx2 v[172:173], v[192:193], off offset:96
	global_load_dwordx2 v[174:175], v[192:193], off offset:112
	global_load_dwordx4 v[176:179], v[194:195], off
	global_load_dwordx4 v[180:183], v[194:195], off offset:32
	global_load_dwordx4 v[184:187], v[194:195], off offset:64
	global_load_dwordx4 v[188:191], v[194:195], off offset:96
	v_rcp_f32_e32 v34, v34
	s_waitcnt lgkmcnt(1)
	v_mfma_f32_32x32x16_bf16 v[16:31], v[36:39], v[40:43], v[16:31]
	ds_read2_b64 v[36:39], v45 offset0:100 offset1:102
	s_waitcnt lgkmcnt(1)
	v_mfma_f32_32x32x16_bf16 v[0:15], v[4:7], v[0:3], 0
	s_waitcnt lgkmcnt(0)
	v_mfma_f32_32x32x16_bf16 v[0:15], v[36:39], v[40:43], v[0:15]
	ds_read2_b64 v[40:43], v44 offset0:8 offset1:10
	v_cvt_pk_bf16_f32 v36, v70, v71
	v_cvt_pk_bf16_f32 v37, v72, v73
	v_cvt_pk_bf16_f32 v38, v74, v75
	v_cvt_pk_bf16_f32 v39, v76, v77
	s_waitcnt lgkmcnt(0)
	s_nop 0
	v_mfma_f32_32x32x16_bf16 v[16:31], v[40:43], v[36:39], v[16:31]
	ds_read2_b64 v[40:43], v45 offset0:104 offset1:106
	s_waitcnt lgkmcnt(0)
	v_mfma_f32_32x32x16_bf16 v[0:15], v[40:43], v[36:39], v[0:15]
	ds_read2_b64 v[40:43], v44 offset0:12 offset1:14
	v_cvt_pk_bf16_f32 v36, v83, v81
	v_cvt_pk_bf16_f32 v37, v82, v78
	v_cvt_pk_bf16_f32 v38, v79, v61
	v_cvt_pk_bf16_f32 v39, v62, v59
	s_waitcnt lgkmcnt(0)
	s_nop 0
	v_mfma_f32_32x32x16_bf16 v[16:31], v[40:43], v[36:39], v[16:31]
	ds_read2_b64 v[40:43], v45 offset0:108 offset1:110
	s_waitcnt lgkmcnt(0)
	v_mfma_f32_32x32x16_bf16 v[0:15], v[40:43], v[36:39], v[0:15]
	ds_read2_b64 v[40:43], v44 offset0:16 offset1:18
	v_cvt_pk_bf16_f32 v36, v60, v57
	v_cvt_pk_bf16_f32 v37, v58, v55
	v_cvt_pk_bf16_f32 v38, v56, v53
	v_cvt_pk_bf16_f32 v39, v54, v52
	s_waitcnt lgkmcnt(0)
	s_nop 0
	v_mfma_f32_32x32x16_bf16 v[16:31], v[40:43], v[36:39], v[16:31]
	ds_read2_b64 v[40:43], v45 offset0:112 offset1:114
	s_waitcnt lgkmcnt(0)
	v_mfma_f32_32x32x16_bf16 v[0:15], v[40:43], v[36:39], v[0:15]
	ds_read2_b64 v[40:43], v44 offset0:20 offset1:22
	v_cvt_pk_bf16_f32 v36, v51, v50
	v_cvt_pk_bf16_f32 v37, v49, v48
	v_cvt_pk_bf16_f32 v38, v84, v85
	v_cvt_pk_bf16_f32 v39, v86, v87
	s_waitcnt lgkmcnt(0)
	s_nop 0
	v_mfma_f32_32x32x16_bf16 v[16:31], v[40:43], v[36:39], v[16:31]
	ds_read2_b64 v[40:43], v45 offset0:116 offset1:118
	s_waitcnt lgkmcnt(0)
	v_mfma_f32_32x32x16_bf16 v[0:15], v[40:43], v[36:39], v[0:15]
	ds_read2_b64 v[40:43], v44 offset0:24 offset1:26
	v_cvt_pk_bf16_f32 v36, v88, v89
	v_cvt_pk_bf16_f32 v37, v90, v91
	v_cvt_pk_bf16_f32 v38, v35, v92
	v_cvt_pk_bf16_f32 v39, v33, v32
	s_waitcnt lgkmcnt(0)
	s_nop 0
	v_mfma_f32_32x32x16_bf16 v[16:31], v[40:43], v[36:39], v[16:31]
	ds_read2_b64 v[40:43], v45 offset0:120 offset1:122
	s_waitcnt lgkmcnt(0)
	v_mfma_f32_32x32x16_bf16 v[0:15], v[40:43], v[36:39], v[0:15]
	ds_read2_b64 v[40:43], v44 offset0:28 offset1:30
	v_cvt_pk_bf16_f32 v36, v93, v94
	v_cvt_pk_bf16_f32 v37, v95, v96
	v_cvt_pk_bf16_f32 v38, v137, v138
	v_cvt_pk_bf16_f32 v39, v139, v140
	s_waitcnt lgkmcnt(0)
	s_nop 0
	v_mfma_f32_32x32x16_bf16 v[16:31], v[40:43], v[36:39], v[16:31]
	ds_read2_b64 v[40:43], v45 offset0:124 offset1:126
	s_waitcnt lgkmcnt(0)
	v_mfma_f32_32x32x16_bf16 v[0:15], v[40:43], v[36:39], v[0:15]
	ds_read2_b64 v[40:43], v44 offset0:32 offset1:34
	v_cvt_pk_bf16_f32 v36, v141, v142
	v_cvt_pk_bf16_f32 v37, v143, v144
	v_cvt_pk_bf16_f32 v38, v145, v146
	v_cvt_pk_bf16_f32 v39, v147, v148
	s_waitcnt lgkmcnt(0)
	s_nop 0
	v_mfma_f32_32x32x16_bf16 v[16:31], v[40:43], v[36:39], v[16:31]
	ds_read2_b64 v[40:43], v45 offset0:128 offset1:130
	s_add_u32 s36, s36, 4
	s_addc_u32 s37, s37, 0
	s_mov_b64 s[0:1], 0x80
	s_cmp_eq_u32 s38, 8
	s_waitcnt lgkmcnt(0)
	v_mfma_f32_32x32x16_bf16 v[0:15], v[40:43], v[36:39], v[0:15]
	ds_read2_b64 v[40:43], v44 offset0:36 offset1:38
	v_cvt_pk_bf16_f32 v36, v149, v150
	v_cvt_pk_bf16_f32 v37, v151, v152
	v_cvt_pk_bf16_f32 v38, v153, v154
	v_cvt_pk_bf16_f32 v39, v155, v156
	s_waitcnt lgkmcnt(0)
	s_nop 0
	v_mfma_f32_32x32x16_bf16 v[16:31], v[40:43], v[36:39], v[16:31]
	ds_read2_b64 v[40:43], v45 offset0:132 offset1:134
	s_waitcnt lgkmcnt(0)
	v_mfma_f32_32x32x16_bf16 v[0:15], v[40:43], v[36:39], v[0:15]
	s_nop 0
	s_nop 0
	s_nop 6
	v_pk_mul_f32 v[16:17], v[16:17], v[34:35] op_sel_hi:[1,0]
	v_pk_mul_f32 v[18:19], v[18:19], v[34:35] op_sel_hi:[1,0]
	s_nop 0
	v_pk_mul_f32 v[0:1], v[0:1], v[34:35] op_sel_hi:[1,0]
	v_pk_mul_f32 v[2:3], v[2:3], v[34:35] op_sel_hi:[1,0]
	s_waitcnt vmcnt(11)
	v_lshlrev_b32_e32 v50, 16, v160
	v_and_b32_e32 v51, 0xffff0000, v160
	v_lshlrev_b32_e32 v48, 16, v161
	v_and_b32_e32 v49, 0xffff0000, v161
	v_pk_mul_f32 v[16:17], v[16:17], v[50:51]
	v_pk_mul_f32 v[18:19], v[18:19], v[48:49]
	v_cvt_pk_bf16_f32 v16, v16, v17
	v_cvt_pk_bf16_f32 v17, v18, v19
	global_store_dwordx2 v[102:103], v[16:17], off offset:-64
	v_pk_mul_f32 v[16:17], v[20:21], v[34:35] op_sel_hi:[1,0]
	s_waitcnt vmcnt(11)
	v_lshlrev_b32_e32 v18, 16, v162
	v_and_b32_e32 v19, 0xffff0000, v162
	v_pk_mul_f32 v[16:17], v[16:17], v[18:19]
	v_pk_mul_f32 v[18:19], v[22:23], v[34:35] op_sel_hi:[1,0]
	v_lshlrev_b32_e32 v20, 16, v163
	v_and_b32_e32 v21, 0xffff0000, v163
	v_pk_mul_f32 v[18:19], v[18:19], v[20:21]
	v_cvt_pk_bf16_f32 v16, v16, v17
	v_cvt_pk_bf16_f32 v17, v18, v19
	global_store_dwordx2 v[102:103], v[16:17], off offset:-48
	v_pk_mul_f32 v[16:17], v[24:25], v[34:35] op_sel_hi:[1,0]
	s_waitcnt vmcnt(11)
	v_lshlrev_b32_e32 v18, 16, v164
	v_and_b32_e32 v19, 0xffff0000, v164
	v_pk_mul_f32 v[16:17], v[16:17], v[18:19]
	v_pk_mul_f32 v[18:19], v[26:27], v[34:35] op_sel_hi:[1,0]
	v_lshlrev_b32_e32 v20, 16, v165
	v_and_b32_e32 v21, 0xffff0000, v165
	v_pk_mul_f32 v[18:19], v[18:19], v[20:21]
	v_cvt_pk_bf16_f32 v16, v16, v17
	v_cvt_pk_bf16_f32 v17, v18, v19
	global_store_dwordx2 v[102:103], v[16:17], off offset:-32
	v_pk_mul_f32 v[16:17], v[28:29], v[34:35] op_sel_hi:[1,0]
	s_waitcnt vmcnt(11)
	v_lshlrev_b32_e32 v18, 16, v166
	v_and_b32_e32 v19, 0xffff0000, v166
	v_pk_mul_f32 v[16:17], v[16:17], v[18:19]
	v_pk_mul_f32 v[18:19], v[30:31], v[34:35] op_sel_hi:[1,0]
	v_lshlrev_b32_e32 v20, 16, v167
	v_and_b32_e32 v21, 0xffff0000, v167
	v_pk_mul_f32 v[18:19], v[18:19], v[20:21]
	v_cvt_pk_bf16_f32 v16, v16, v17
	v_cvt_pk_bf16_f32 v17, v18, v19
	global_store_dwordx2 v[102:103], v[16:17], off offset:-16
	s_waitcnt vmcnt(11)
	v_lshlrev_b32_e32 v16, 16, v168
	v_and_b32_e32 v17, 0xffff0000, v168
	v_pk_mul_f32 v[0:1], v[0:1], v[16:17]
	v_lshlrev_b32_e32 v16, 16, v169
	v_and_b32_e32 v17, 0xffff0000, v169
	v_pk_mul_f32 v[2:3], v[2:3], v[16:17]
	v_cvt_pk_bf16_f32 v0, v0, v1
	v_cvt_pk_bf16_f32 v1, v2, v3
	global_store_dwordx2 v[102:103], v[0:1], off
	v_pk_mul_f32 v[0:1], v[4:5], v[34:35] op_sel_hi:[1,0]
	s_waitcnt vmcnt(11)
	v_lshlrev_b32_e32 v2, 16, v170
	v_and_b32_e32 v3, 0xffff0000, v170
	v_pk_mul_f32 v[0:1], v[0:1], v[2:3]
	v_pk_mul_f32 v[2:3], v[6:7], v[34:35] op_sel_hi:[1,0]
	v_lshlrev_b32_e32 v4, 16, v171
	v_and_b32_e32 v5, 0xffff0000, v171
	v_pk_mul_f32 v[2:3], v[2:3], v[4:5]
	v_cvt_pk_bf16_f32 v0, v0, v1
	v_cvt_pk_bf16_f32 v1, v2, v3
	global_store_dwordx2 v[102:103], v[0:1], off offset:16
	v_pk_mul_f32 v[0:1], v[8:9], v[34:35] op_sel_hi:[1,0]
	s_waitcnt vmcnt(11)
	v_lshlrev_b32_e32 v2, 16, v172
	v_and_b32_e32 v3, 0xffff0000, v172
	v_pk_mul_f32 v[0:1], v[0:1], v[2:3]
	v_pk_mul_f32 v[2:3], v[10:11], v[34:35] op_sel_hi:[1,0]
	v_lshlrev_b32_e32 v4, 16, v173
	v_and_b32_e32 v5, 0xffff0000, v173
	v_pk_mul_f32 v[2:3], v[2:3], v[4:5]
	v_cvt_pk_bf16_f32 v0, v0, v1
	v_cvt_pk_bf16_f32 v1, v2, v3
	global_store_dwordx2 v[102:103], v[0:1], off offset:32
	v_pk_mul_f32 v[0:1], v[12:13], v[34:35] op_sel_hi:[1,0]
	s_waitcnt vmcnt(11)
	v_lshlrev_b32_e32 v2, 16, v174
	v_and_b32_e32 v3, 0xffff0000, v174
	v_pk_mul_f32 v[0:1], v[0:1], v[2:3]
	v_pk_mul_f32 v[2:3], v[14:15], v[34:35] op_sel_hi:[1,0]
	v_lshlrev_b32_e32 v4, 16, v175
	v_and_b32_e32 v5, 0xffff0000, v175
	v_pk_mul_f32 v[2:3], v[2:3], v[4:5]
	v_cvt_pk_bf16_f32 v0, v0, v1
	v_cvt_pk_bf16_f32 v1, v2, v3
	global_store_dwordx2 v[102:103], v[0:1], off offset:48
	v_lshl_add_u64 v[102:103], v[102:103], 0, s[0:1]
	s_waitcnt vmcnt(8)
	v_mov_b32_e32 v80, v176
	v_mov_b32_e32 v81, v177
	v_mov_b32_e32 v82, v178
	v_mov_b32_e32 v83, v179
	v_mov_b32_e32 v84, v180
	v_mov_b32_e32 v85, v181
	v_mov_b32_e32 v86, v182
	v_mov_b32_e32 v87, v183
	v_mov_b32_e32 v88, v184
	v_mov_b32_e32 v89, v185
	v_mov_b32_e32 v90, v186
	v_mov_b32_e32 v91, v187
	v_mov_b32_e32 v92, v188
	v_mov_b32_e32 v93, v189
	v_mov_b32_e32 v94, v190
	v_mov_b32_e32 v95, v191
	s_cbranch_scc0 .LBB0_2056
	v_readlane_b32 s91, v254, 17
	v_readlane_b32 s24, v254, 52
	s_mov_b32 s37, s3
	s_movk_i32 s25, 0x90
	s_branch .LBB0_1999
